# speedup vs baseline: 1.0064x; 1.0041x over previous
; #define LAS __attribute__((address_space(3)))
; template <int LDQ, int LDK, int LDV, int LDO>
; __device__ __forceinline__ void attn256_body(const int tid, const bf16_t* __restrict__ Qb, const bf16_t* __restrict__ Kh, const bf16_t* __restrict__ Vh, bf16_t* __restrict__ Ob, int seq, char* lds, LAS unsigned char* ldsl) {
;     const int wid = __builtin_amdgcn_readfirstlane(tid >> 6), lane = tid & 63, r32 = lane & 31, hi = lane >> 5;
;     float* wsf = (float*)(lds + A2_SCR) + wid * 64; float* li_l = wsf; float* al_l = wsf + 32;
;     float m_reg = -1e30f, l_reg = 0; f32x16 o[8] = {}; bf16x8 qr[8];
;     unsigned kof[2], vof[4];
; #pragma unroll
;     for (int i = 0; i < 2; ++i) { const int q = (i * 8 + wid) * 64 + lane, row = q >> 4, chunk = (q & 15) ^ (row & 7); kof[i] = (unsigned)(row * LDK + chunk * 8) * 2u; }
; #pragma unroll
;     for (int i = 0; i < 4; ++i) { const int q = (i * 8 + wid) * 64 + lane, half = q >> 10, qq = q & 1023, sub = qq >> 5, kk = (sub >> 2) * 8 + ((qq >> 2) & 7), c = (sub & 3) * 32 + (qq & 3) * 8;
; __device__ __forceinline__ void mix_phase(const int tid0, const P& p, int l, char* lds, const int per_q, const int cl) {
;     ...
;         const int xq = item >> 9, idx = item & 511;
;         if (idx < 12) { mlstm_item(tid, p, xq * 12 + idx, lds); }
;         else if (idx >= 108) {
;             const int t = xq * 258 + (idx - 108);
;             if (t < CT_UP) convert_tile(tid, (float*)lds, p.in[18] + (size_t)cl * DM * DFF, p.in[19] + (size_t)cl * DM * DFF, p.in[17] + (size_t)cl * DM, (bf16_t*)(p.ws + WS_WUP2), DM, DFF, 1, t);
;             else convert_tile(tid, (float*)lds, p.in[20] + (size_t)cl * DFF * DM, nullptr, nullptr, (bf16_t*)(p.ws + WS_WDN2), DFF, DM, 0, t - CT_UP);
;             __syncthreads();
;         }
;         else {
;             const int g = xq * 6 + ((idx - 12) >> 4), qblk = (idx - 12) & 15, comp = g & 1, head = (g >> 1) & 3, b = g >> 3;
;             const bf16_t* Q = qka + (size_t)(b * SEQ + qblk * 256) * 2048 + head * 256 + comp * 128;
;             const bf16_t* Kp = qka + (size_t)(b * SEQ) * 2048 + 1024 + head * 256 + comp * 128;
;             const bf16_t* Vp = z + (size_t)(b * SEQ) * ZLD + 6144 + head * 256;
;             bf16_t* O = z + (size_t)(b * SEQ + qblk * 256) * ZLD + 4096 + comp * 1024 + head * 256;
;             attn256_body<2048, 2048, ZLD, ZLD>(tid, Q, Kp, Vp, O, SEQ, lds, (LAS unsigned char*)lds);
.LBB0_130:
	s_or_b64 exec, exec, s[0:1]
	v_mov_b32_e32 v0, s33
	s_waitcnt lgkmcnt(0)
	s_barrier
	ds_read_b32 v0, v0
	s_waitcnt lgkmcnt(0)
	s_barrier
	v_cmp_gt_i32_e32 vcc, 0, v0
	v_readfirstlane_b32 s8, v0
	s_cbranch_vccnz .LBB0_142
	s_lshr_b32 s9, s8, 9
	s_and_b32 s14, s8, 0x1ff
	s_cmp_gt_u32 s14, 11
	s_mov_b64 s[0:1], -1
	s_cbranch_scc0 .LBB0_155
	s_cmpk_lt_u32 s14, 0x6c
	s_cbranch_scc0 .LBB0_146
	s_add_i32 s1, s14, -12
	s_mul_i32 s0, s9, 6
	s_lshr_b32 s4, s1, 4
	s_add_i32 s25, s4, s0
	s_lshl_b32 s0, s25, 9
	s_and_b32 s4, s0, 0x7ffff000
	s_lshl_b32 s0, s1, 8
	s_and_b32 s0, s0, 0xf00
	s_or_b32 s30, s4, s0
	s_bfe_u32 s15, s1, 0x10004
	s_lshl_b64 s[0:1], s[30:31], 12
	s_add_u32 s0, s54, s0
	s_addc_u32 s1, s67, s1
	s_lshl_b32 s5, s25, 7
	s_and_b32 s16, s5, 0x300
	s_lshl_b32 s17, s16, 1
	s_add_u32 s0, s0, s17
	s_addc_u32 s1, s1, 0
	s_lshl_b32 s24, s15, 8
	s_add_u32 s0, s0, s24
	s_mov_b32 s5, s31
	s_addc_u32 s1, s1, 0
	s_lshl_b64 s[6:7], s[4:5], 12
	s_add_u32 s5, s54, s6
	s_addc_u32 s21, s67, s7
	s_add_u32 s5, s5, s17
	s_addc_u32 s21, s21, 0
	s_add_u32 s22, s5, s24
	s_addc_u32 s23, s21, 0
	s_mul_i32 s36, s4, 0x3800
	s_mul_hi_u32 s28, s4, 0x3800
	s_add_u32 s4, s93, s36
	v_readfirstlane_b32 s21, v208
	s_addc_u32 s5, s66, s28
	s_movk_i32 s38, 0xffc0
	v_mov_b32_e32 v0, s21
	s_add_u32 s4, s4, s17
	v_bfi_b32 v2, s38, v0, v209
	s_addc_u32 s5, s5, 0
	v_and_b32_e32 v3, 15, v209
	v_ashrrev_i32_e32 v0, 4, v2
	v_add_u32_e32 v2, 0x200, v2
	s_add_u32 s4, s4, 0x3000
	v_bitop3_b32 v4, v0, v3, 15 bitop3:0x6c
	v_lshlrev_b32_e32 v0, 12, v0
	v_ashrrev_i32_e32 v2, 4, v2
	s_addc_u32 s5, s5, 0
	s_and_b32 s37, s21, 0xffffffc0
	v_lshl_or_b32 v0, v4, 4, v0
	v_bitop3_b32 v3, v2, v3, 15 bitop3:0x6c
	v_lshlrev_b32_e32 v2, 12, v2
	v_lshrrev_b32_e32 v4, 1, v208
	s_lshr_b32 s46, s21, 5
	v_lshl_or_b32 v2, v3, 4, v2
	v_bfe_u32 v3, v208, 2, 2
	v_and_b32_e32 v4, 8, v4
	s_and_b32 s46, s46, 4
	s_add_i32 s47, s37, 0x200
	v_lshlrev_b32_e32 v8, 3, v209
	v_or3_b32 v3, v4, v3, s46
	s_lshr_b32 s48, s47, 4
	s_lshl_b32 s17, s37, 2
	s_and_b32 s38, s21, 64
	v_and_b32_e32 v7, 32, v209
	v_and_b32_e32 v9, 24, v8
	s_lshr_b32 s46, s21, 4
	v_and_or_b32 v12, s48, 48, v3
	s_ashr_i32 s47, s47, 3
	s_add_i32 s48, s21, 0x400
	s_addk_i32 s37, 0x600
	v_or3_b32 v4, v9, v7, s38
	v_and_or_b32 v10, s46, 48, v3
	s_ashr_i32 s46, s21, 3
	s_and_b32 s47, s47, 0xffffff80
	s_ashr_i32 s48, s48, 3
	s_lshr_b32 s49, s37, 4
	s_ashr_i32 s37, s37, 3
	s_and_b32 s46, s46, 0xffffff80
	v_mul_u32_u24_e32 v13, 0x1c00, v12
	v_or_b32_e32 v14, s47, v4
	s_and_b32 s48, s48, 0xffffff80
	v_and_or_b32 v15, s49, 48, v3
	s_and_b32 s49, s37, 0xffffff80
	s_ashr_i32 s37, s21, 6
	v_mul_u32_u24_e32 v5, 0x1c00, v10
	v_or_b32_e32 v11, s46, v4
	v_add_lshl_u32 v13, v14, v13, 1
	v_or_b32_e32 v14, s48, v4
	v_mul_u32_u24_e32 v3, 0x1c00, v15
	v_or_b32_e32 v4, s49, v4
	s_lshl_b32 s21, s37, 10
	v_add_lshl_u32 v11, v11, v5, 1
	v_add_lshl_u32 v14, v14, v5, 1
	v_add_lshl_u32 v16, v4, v3, 1
	s_add_i32 s21, s21, 0
	v_lshl_add_u64 v[4:5], s[22:23], 0, v[0:1]
	s_mov_b64 s[56:57], 0x800
	v_lshl_add_u64 v[4:5], v[4:5], 0, s[56:57]
	s_mov_b32 m0, s21
	v_mov_b32_e32 v3, v1
	global_load_lds_dwordx4 v[4:5], off
	v_lshl_add_u64 v[4:5], s[22:23], 0, v[2:3]
	v_and_b32_e32 v211, 31, v209
	v_lshl_add_u64 v[4:5], v[4:5], 0, s[56:57]
	s_add_i32 m0, s21, 0x2000
	s_lshl_b32 s22, s37, 5
	global_load_lds_dwordx4 v[4:5], off
	s_add_i32 m0, s21, 0x8000
	v_or_b32_e32 v4, s22, v211
	global_load_lds_dwordx4 v11, s[4:5]
	s_add_i32 m0, s21, 0xa000
	v_ashrrev_i32_e32 v5, 31, v4
	v_bfe_u32 v210, v209, 5, 1
	global_load_lds_dwordx4 v13, s[4:5]
	s_add_i32 m0, s21, 0xc000
	v_lshlrev_b64 v[4:5], 12, v[4:5]
	global_load_lds_dwordx4 v14, s[4:5]
	s_add_i32 m0, s21, 0xe000
	v_lshl_add_u64 v[4:5], s[0:1], 0, v[4:5]
	v_lshlrev_b32_e32 v194, 4, v210
	v_mov_b32_e32 v195, v1
	global_load_lds_dwordx4 v16, s[4:5]
	v_lshl_add_u64 v[4:5], v[4:5], 0, v[194:195]
	global_load_dwordx4 v[162:165], v[4:5], off
	global_load_dwordx4 v[166:169], v[4:5], off offset:32
	global_load_dwordx4 v[170:173], v[4:5], off offset:64
	global_load_dwordx4 v[174:177], v[4:5], off offset:96
	global_load_dwordx4 v[178:181], v[4:5], off offset:128
	global_load_dwordx4 v[182:185], v[4:5], off offset:160
	global_load_dwordx4 v[186:189], v[4:5], off offset:192
	global_load_dwordx4 v[190:193], v[4:5], off offset:224
	v_lshlrev_b32_e32 v4, 4, v209
	v_and_b32_e32 v13, 0xf0, v4
	s_movk_i32 s0, 0x60
	v_bitop3_b32 v215, v194, v13, s0 bitop3:0x36
	s_movk_i32 s0, 0xa0
	s_add_i32 s17, s17, 0
	v_bitop3_b32 v218, v194, v13, s0 bitop3:0x36
	s_movk_i32 s0, 0xc0
	s_add_i32 s17, s17, 0x18000
	v_lshlrev_b32_e32 v11, 1, v209
	v_bitop3_b32 v219, v194, v13, s0 bitop3:0x36
	s_movk_i32 s0, 0xe0
	v_and_b32_e32 v11, 32, v11
	v_bitop3_b32 v220, v194, v13, s0 bitop3:0x36
	s_movk_i32 s0, 0x118
	s_cmp_lg_u32 0, -1
	v_and_b32_e32 v5, 0xc0, v4
	v_xor_b32_e32 v212, v194, v13
	v_and_or_b32 v4, v8, s0, v11
	s_cselect_b32 s0, 0, 0
	s_add_i32 s0, s0, 0x8000
	v_add3_u32 v221, v5, s0, v4
	s_lshl_b32 s0, s25, 8
	s_or_b32 s25, s38, s46
	v_mov_b32_e32 v4, s25
	s_movk_i32 s46, 0x1c00
	s_and_b32 s0, s0, 0x600
	v_mad_u32_u24 v4, v10, s46, v4
	v_readlane_b32 s25, v255, 17
	v_or3_b32 v4, v4, v7, v9
	s_add_u32 s36, s25, s36
	v_lshlrev_b32_e32 v4, 1, v4
	v_mov_b32_e32 v5, v1
	s_addc_u32 s37, s65, s28
	s_or_b32 s25, s38, s47
	v_lshl_add_u64 v[196:197], s[36:37], 0, v[4:5]
	v_mov_b32_e32 v4, s25
	v_mad_u32_u24 v4, v12, s46, v4
	v_or3_b32 v4, v4, v7, v9
	v_lshlrev_b32_e32 v4, 1, v4
	s_or_b32 s25, s38, s48
	v_lshl_add_u64 v[198:199], s[36:37], 0, v[4:5]
	v_mov_b32_e32 v4, s25
	v_mad_u32_u24 v4, v10, s46, v4
	v_or3_b32 v4, v4, v7, v9
	v_lshlrev_b32_e32 v4, 1, v4
	s_or_b32 s25, s38, s49
; __device__ __forceinline__ int v_rd_base(int lane) { return ((lane & 3) << 3) | (((lane >> 2) & 3) << 6) | (((lane >> 4) & 1) << 5) | (((lane >> 5) & 1) << 8); }
; template <int LDQ, int LDK, int LDV, int LDO>
; __device__ __forceinline__ void attn256_body(const int tid, const bf16_t* __restrict__ Qb, const bf16_t* __restrict__ Kh, const bf16_t* __restrict__ Vh, bf16_t* __restrict__ Ob, int seq, char* lds, LAS unsigned char* ldsl) {
;     ...
;     float m_reg = -1e30f, l_reg = 0; f32x16 o[8] = {}; bf16x8 qr[8];
;     unsigned kof[2], vof[4];
; #pragma unroll
;     for (int i = 0; i < 2; ++i) { const int q = (i * 8 + wid) * 64 + lane, row = q >> 4, chunk = (q & 15) ^ (row & 7); kof[i] = (unsigned)(row * LDK + chunk * 8) * 2u; }
; #pragma unroll
;     for (int i = 0; i < 4; ++i) { const int q = (i * 8 + wid) * 64 + lane, half = q >> 10, qq = q & 1023, sub = qq >> 5, kk = (sub >> 2) * 8 + ((qq >> 2) & 7), c = (sub & 3) * 32 + (qq & 3) * 8;
;         const int k = (kk & ~0xC) | ((kk & 4) << 1) | ((kk & 8) >> 1); vof[i] = (unsigned)(k * LDV + half * 128 + c) * 2u; }
;     ...
;     A2_ISSUE(0, 0);
;     { const bf16_t* Qw = Qb + (long)(wid * 32 + r32) * LDQ + hi * 8;
; #pragma unroll
;       for (int d0 = 0; d0 < 8; ++d0) qr[d0] = *reinterpret_cast<const bf16x8*>(Qw + d0 * 16); }
;     const int vb0 = (int)(uintptr_t)(lds + A2_VOFF) + v_rd_base(lane);
;     const int NT = seq / 64;
;     constexpr float C = ATT_SCALE * 1.4426950408889634f;
;     for (int j = 0; j < NT; ++j) {
;         const int b = j & 1;
;         asm volatile("s_waitcnt vmcnt(0)" ::: "memory"); __builtin_amdgcn_s_barrier(); asm volatile("" ::: "memory");
;         if (j + 1 < NT) A2_ISSUE(j + 1, b ^ 1);
;         f32x16 p0, p1;
;         qkt(p0, p1, lds + A2_KOFF + b * 16384, qr, r32, hi);
	v_lshl_add_u64 v[200:201], s[36:37], 0, v[4:5]
	v_mov_b32_e32 v4, s25
	v_mad_u32_u24 v4, v15, s46, v4
	s_or_b32 s6, s6, s24
	v_or3_b32 v4, v4, v7, v9
	s_add_u32 s6, s92, s6
	v_and_b32_e32 v6, 63, v209
	v_lshlrev_b32_e32 v4, 1, v4
	s_addc_u32 s7, s51, s7
	v_mov_b32_e32 v14, v1
	v_mov_b32_e32 v15, v1
	v_bitop3_b32 v213, v194, v13, 32 bitop3:0x36
	v_bitop3_b32 v214, v194, v13, 64 bitop3:0x36
	v_bitop3_b32 v216, v194, v13, s88 bitop3:0x36
	v_cmp_gt_u32_e64 s[4:5], 32, v6
	v_lshl_add_u64 v[202:203], s[36:37], 0, v[4:5]
	v_lshl_add_u64 v[204:205], s[6:7], 0, v[2:3]
	v_lshl_add_u64 v[206:207], s[6:7], 0, v[0:1]
	v_mov_b32_e32 v0, v1
	v_mov_b32_e32 v2, v1
	v_mov_b32_e32 v4, v1
	v_mov_b32_e32 v6, v1
	v_mov_b32_e32 v7, v1
	v_mov_b32_e32 v8, v1
	v_mov_b32_e32 v9, v1
	v_mov_b32_e32 v10, v1
	v_mov_b32_e32 v11, v1
	v_mov_b32_e32 v12, v1
	v_mov_b32_e32 v13, v1
	v_mov_b64_e32 v[128:129], v[14:15]
	v_mov_b64_e32 v[112:113], v[14:15]
	v_mov_b64_e32 v[96:97], v[14:15]
	v_mov_b64_e32 v[80:81], v[14:15]
	v_mov_b64_e32 v[64:65], v[14:15]
	v_mov_b64_e32 v[48:49], v[14:15]
	v_mov_b64_e32 v[32:33], v[14:15]
	v_mov_b64_e32 v[126:127], v[12:13]
	v_mov_b64_e32 v[124:125], v[10:11]
	v_mov_b64_e32 v[122:123], v[8:9]
	v_mov_b64_e32 v[120:121], v[6:7]
	v_mov_b64_e32 v[118:119], v[4:5]
	v_mov_b64_e32 v[116:117], v[2:3]
	v_mov_b64_e32 v[114:115], v[0:1]
	v_mov_b64_e32 v[110:111], v[12:13]
	v_mov_b64_e32 v[108:109], v[10:11]
	v_mov_b64_e32 v[106:107], v[8:9]
	v_mov_b64_e32 v[104:105], v[6:7]
	v_mov_b64_e32 v[102:103], v[4:5]
	v_mov_b64_e32 v[100:101], v[2:3]
	v_mov_b64_e32 v[98:99], v[0:1]
	v_mov_b64_e32 v[94:95], v[12:13]
	v_mov_b64_e32 v[92:93], v[10:11]
	v_mov_b64_e32 v[90:91], v[8:9]
	v_mov_b64_e32 v[88:89], v[6:7]
	v_mov_b64_e32 v[86:87], v[4:5]
	v_mov_b64_e32 v[84:85], v[2:3]
	v_mov_b64_e32 v[82:83], v[0:1]
	v_mov_b64_e32 v[78:79], v[12:13]
	v_mov_b64_e32 v[76:77], v[10:11]
	v_mov_b64_e32 v[74:75], v[8:9]
	v_mov_b64_e32 v[72:73], v[6:7]
	v_mov_b64_e32 v[70:71], v[4:5]
	v_mov_b64_e32 v[68:69], v[2:3]
	v_mov_b64_e32 v[66:67], v[0:1]
	v_mov_b64_e32 v[62:63], v[12:13]
	v_mov_b64_e32 v[60:61], v[10:11]
	v_mov_b64_e32 v[58:59], v[8:9]
	v_mov_b64_e32 v[56:57], v[6:7]
	v_mov_b64_e32 v[54:55], v[4:5]
	v_mov_b64_e32 v[52:53], v[2:3]
	v_mov_b64_e32 v[50:51], v[0:1]
	v_mov_b64_e32 v[46:47], v[12:13]
	v_mov_b64_e32 v[44:45], v[10:11]
	v_mov_b64_e32 v[42:43], v[8:9]
	v_mov_b64_e32 v[40:41], v[6:7]
	v_mov_b64_e32 v[38:39], v[4:5]
	v_mov_b64_e32 v[36:37], v[2:3]
	v_mov_b64_e32 v[34:35], v[0:1]
	v_mov_b64_e32 v[30:31], v[12:13]
	v_mov_b64_e32 v[28:29], v[10:11]
	v_mov_b64_e32 v[26:27], v[8:9]
	v_mov_b64_e32 v[24:25], v[6:7]
	v_mov_b64_e32 v[22:23], v[4:5]
	v_mov_b64_e32 v[20:21], v[2:3]
	v_mov_b64_e32 v[18:19], v[0:1]
	v_mov_b64_e32 v[16:17], v[14:15]
	v_lshlrev_b32_e32 v195, 8, v211
	v_lshl_add_u32 v217, v211, 2, s17
	s_mov_b32 s23, 0
	s_mov_b32 s1, s31
	v_mov_b32_e32 v223, 0
	v_mov_b32_e32 v222, 0xf149f2ca
	v_mov_b64_e32 v[14:15], v[12:13]
	v_mov_b64_e32 v[12:13], v[10:11]
	v_mov_b64_e32 v[10:11], v[8:9]
	v_mov_b64_e32 v[8:9], v[6:7]
	v_mov_b64_e32 v[6:7], v[4:5]
	v_mov_b64_e32 v[4:5], v[2:3]
	v_mov_b64_e32 v[2:3], v[0:1]
	s_waitcnt vmcnt(0)
	v_add_u32_e32 v212, v212, v195
	v_add_u32_e32 v213, v213, v195
	v_add_u32_e32 v214, v214, v195
	v_add_u32_e32 v215, v215, v195
	v_add_u32_e32 v216, v216, v195
	v_add_u32_e32 v218, v218, v195
	v_add_u32_e32 v219, v219, v195
	v_add_u32_e32 v220, v220, v195
	v_subrev_u32_e32 v204, s6, v204
	v_subrev_u32_e32 v206, s6, v206
	v_subrev_u32_e32 v196, s36, v196
	v_subrev_u32_e32 v198, s36, v198
	v_subrev_u32_e32 v200, s36, v200
	v_subrev_u32_e32 v202, s36, v202
	s_add_u32 s6, s6, s0
	s_addc_u32 s7, s7, s1
	s_add_u32 s36, s36, s0
	s_addc_u32 s37, s37, s1
	s_waitcnt vmcnt(0)
	s_barrier
	ds_read_b128 v[224:227], v212
	ds_read_b128 v[228:231], v213
	ds_read_b128 v[232:235], v214
	ds_read_b128 v[236:239], v215
	ds_read_b128 v[244:247], v216
	ds_read_b128 v[248:251], v218
.LBB0_134:
	s_add_i32 m0, s21, 0x4000
	s_nop 0
	global_load_lds_dwordx4 v206, s[6:7]
	s_add_i32 m0, s21, 0x6000
	s_nop 0
	global_load_lds_dwordx4 v204, s[6:7]
	s_add_i32 m0, s21, 0x10000
	s_nop 0
	global_load_lds_dwordx4 v196, s[36:37]
	s_add_i32 m0, s21, 0x12000
	s_nop 0
	global_load_lds_dwordx4 v198, s[36:37]
	s_add_i32 m0, s21, 0x14000
	s_nop 0
	global_load_lds_dwordx4 v200, s[36:37]
	s_add_i32 m0, s21, 0x16000
	s_nop 0
	global_load_lds_dwordx4 v202, s[36:37]
	s_waitcnt lgkmcnt(2)
	v_mfma_f32_32x32x16_bf16 v[130:145], v[224:227], v[162:165], 0
	ds_read_b128 v[224:227], v219
	v_mfma_f32_32x32x16_bf16 v[130:145], v[228:231], v[166:169], v[130:145]
	ds_read_b128 v[228:231], v220
	v_mfma_f32_32x32x16_bf16 v[130:145], v[232:235], v[170:173], v[130:145]
	ds_read_b128 v[232:235], v212 offset:8192
	v_mfma_f32_32x32x16_bf16 v[130:145], v[236:239], v[174:177], v[130:145]
	ds_read_b128 v[236:239], v213 offset:8192
	s_waitcnt lgkmcnt(2)
	v_mfma_f32_32x32x16_bf16 v[130:145], v[244:247], v[178:181], v[130:145]
	ds_read_b128 v[244:247], v214 offset:8192
	v_mfma_f32_32x32x16_bf16 v[130:145], v[248:251], v[182:185], v[130:145]
	ds_read_b128 v[248:251], v215 offset:8192
	v_mfma_f32_32x32x16_bf16 v[130:145], v[224:227], v[186:189], v[130:145]
	ds_read_b128 v[224:227], v216 offset:8192
	v_mfma_f32_32x32x16_bf16 v[130:145], v[228:231], v[190:193], v[130:145]
	ds_read_b128 v[228:231], v218 offset:8192
	s_waitcnt lgkmcnt(2)
; __device__ __forceinline__ int crow(int r, int hi) { return (r & 3) + 8 * (r >> 2) + 4 * hi; }
; template <int LDQ, int LDK, int LDV, int LDO>
; __device__ __forceinline__ void attn256_body(const int tid, const bf16_t* __restrict__ Qb, const bf16_t* __restrict__ Kh, const bf16_t* __restrict__ Vh, bf16_t* __restrict__ Ob, int seq, char* lds, LAS unsigned char* ldsl) {
;     ...
;         qkt(p0, p1, lds + A2_KOFF + b * 16384, qr, r32, hi);
;         float pmax = p0[0];
; #pragma unroll
;         for (int r = 1; r < 16; ++r) pmax = fmaxf(pmax, p0[r]);
; #pragma unroll
;         for (int r = 0; r < 16; ++r) pmax = fmaxf(pmax, p1[r]);
;         { auto rr = __builtin_amdgcn_permlane32_swap(__float_as_uint(pmax), __float_as_uint(pmax), false, false); pmax = fmaxf(__uint_as_float(rr[0]), __uint_as_float(rr[1])); }
;         float alpha = 1.f;
;         if (!__all(pmax - m_reg <= ATT_THR / ATT_SCALE)) { const float mn = fmaxf(m_reg, pmax); alpha = __builtin_amdgcn_exp2f((m_reg - mn) * C); m_reg = mn; }
;         const float mnC = -m_reg * C;
;         float ps = 0.f;
; #pragma unroll
;         for (int r = 0; r < 16; ++r) { p0[r] = __builtin_amdgcn_exp2f(fmaf(p0[r], C, mnC)); p1[r] = __builtin_amdgcn_exp2f(fmaf(p1[r], C, mnC)); ps += p0[r] + p1[r]; }
;         { auto rr = __builtin_amdgcn_permlane32_swap(__float_as_uint(ps), __float_as_uint(ps), false, false); ps = __uint_as_float(rr[0]) + __uint_as_float(rr[1]); }
;         l_reg = l_reg * alpha + ps;
;         bf16x8 pa0, pa1, pa2, pa3;
;         PK4(p0, 0, pa0); PK4(p0, 8, pa1); PK4(p1, 0, pa2); PK4(p1, 8, pa3);
;         if (__any(alpha < 1.f)) { if (hi == 0) al_l[r32] = alpha; asm volatile("s_waitcnt lgkmcnt(0)" ::: "memory");
; #pragma unroll
;             for (int r = 0; r < 16; ++r) { const float f = al_l[crow(r, hi)];
; #pragma unroll
;                 for (int d = 0; d < 8; ++d) o[d][r] *= f; } }
;         const int vb = vb0 + b * 32768;
;         pv256(o, vb, pa0, pa1, pa2, pa3);
	v_mfma_f32_32x32x16_bf16 v[146:161], v[232:235], v[162:165], 0
	ds_read_b128 v[232:235], v219 offset:8192
	v_mfma_f32_32x32x16_bf16 v[146:161], v[236:239], v[166:169], v[146:161]
	ds_read_b128 v[236:239], v220 offset:8192
	v_mfma_f32_32x32x16_bf16 v[146:161], v[244:247], v[170:173], v[146:161]
	ds_read_b64_tr_b16 v[244:245], v221 offset:0x0
	ds_read_b64_tr_b16 v[246:247], v221 offset:0x800
	v_mfma_f32_32x32x16_bf16 v[146:161], v[248:251], v[174:177], v[146:161]
	ds_read_b64_tr_b16 v[248:249], v221 offset:0x200
	ds_read_b64_tr_b16 v[250:251], v221 offset:0xa00
	v_max3_f32 v0, v130, v131, v132
	v_max3_f32 v0, v0, v133, v134
	s_waitcnt lgkmcnt(4)
	v_mfma_f32_32x32x16_bf16 v[146:161], v[224:227], v[178:181], v[146:161]
	ds_read_b64_tr_b16 v[224:225], v221 offset:0x400
	ds_read_b64_tr_b16 v[226:227], v221 offset:0xc00
	v_max3_f32 v0, v0, v135, v136
	v_max3_f32 v0, v0, v137, v138
	v_mfma_f32_32x32x16_bf16 v[146:161], v[228:231], v[182:185], v[146:161]
	ds_read_b64_tr_b16 v[228:229], v221 offset:0x600
	ds_read_b64_tr_b16 v[230:231], v221 offset:0xe00
	v_max3_f32 v0, v0, v139, v140
	v_max3_f32 v0, v0, v141, v142
	v_mfma_f32_32x32x16_bf16 v[146:161], v[232:235], v[186:189], v[146:161]
	ds_read_b64_tr_b16 v[232:233], v221 offset:0x4000
	ds_read_b64_tr_b16 v[234:235], v221 offset:0x4800
	v_max3_f32 v0, v0, v143, v144
	v_max_f32_e32 v0, v0, v145
	v_mfma_f32_32x32x16_bf16 v[146:161], v[236:239], v[190:193], v[146:161]
	ds_read_b64_tr_b16 v[236:237], v221 offset:0x4200
	ds_read_b64_tr_b16 v[238:239], v221 offset:0x4a00
	s_add_u32 s6, s6, 0x40000
	s_addc_u32 s7, s7, 0
	s_add_u32 s36, s36, 0xe0000
	s_addc_u32 s37, s37, 0
	s_add_i32 s23, s23, 1
	s_nop 4
	v_max3_f32 v0, v0, v146, v147
	v_max3_f32 v0, v0, v148, v149
	v_max3_f32 v0, v0, v150, v151
	v_max3_f32 v0, v0, v152, v153
	v_max3_f32 v0, v0, v154, v155
	v_max3_f32 v0, v0, v156, v157
	v_max3_f32 v0, v0, v158, v159
	v_max3_f32 v0, v0, v160, v161
	v_mov_b32_e32 v240, v0
	s_nop 1
	v_permlane32_swap_b32_e32 v0, v240
	v_max_f32_e32 v0, v0, v240
	v_sub_f32_e32 v240, v0, v222
	v_cmp_ge_f32_e32 vcc, 0x42b504f3, v240
	s_cmp_eq_u64 vcc, exec
	v_max_f32_e32 v0, v222, v0
	s_cselect_b64 vcc, -1, 0
	v_sub_f32_e32 v240, v222, v0
	v_cndmask_b32_e32 v222, v0, v222, vcc
	v_mul_f32_e32 v240, 0x3e0293ee, v240
	v_mul_f32_e32 v0, 0xbe0293ee, v222
	v_exp_f32_e32 v243, v240
	v_fmamk_f32 v130, v130, 0x3e0293ee, v0
	v_fmamk_f32 v131, v131, 0x3e0293ee, v0
	v_fmamk_f32 v132, v132, 0x3e0293ee, v0
	v_fmamk_f32 v133, v133, 0x3e0293ee, v0
	v_fmamk_f32 v134, v134, 0x3e0293ee, v0
	v_fmamk_f32 v135, v135, 0x3e0293ee, v0
	v_fmamk_f32 v136, v136, 0x3e0293ee, v0
	v_fmamk_f32 v137, v137, 0x3e0293ee, v0
	v_cndmask_b32_e64 v243, v243, 1.0, vcc
	v_cmp_gt_f32_e32 vcc, 1.0, v243
	s_cbranch_vccnz .Lattn_rescale_b0
.Lattn_resc_done_b0:
	v_exp_f32_e32 v130, v130
	v_exp_f32_e32 v131, v131
	v_exp_f32_e32 v132, v132
	v_exp_f32_e32 v133, v133
	v_exp_f32_e32 v134, v134
	v_exp_f32_e32 v135, v135
	v_exp_f32_e32 v136, v136
	v_exp_f32_e32 v137, v137
	v_add_f32_e32 v252, v130, v131
	v_cvt_pk_bf16_f32 v130, v130, v131
	v_add_f32_e32 v208, v132, v133
	v_cvt_pk_bf16_f32 v131, v132, v133
	v_add_f32_e32 v209, v134, v135
	v_cvt_pk_bf16_f32 v132, v134, v135
	v_add_f32_e32 v240, v136, v137
	v_cvt_pk_bf16_f32 v133, v136, v137
	s_nop 0
	v_permlane32_swap_b32_e32 v130, v132
	v_permlane32_swap_b32_e32 v131, v133
	v_add_f32_e32 v252, v252, v208
	v_add_f32_e32 v209, v209, v240
	v_add_f32_e32 v252, v252, v209
	s_waitcnt lgkmcnt(4)
	v_mfma_f32_32x32x16_bf16 v[114:129], v[130:133], v[244:247], v[114:129]
	v_fmamk_f32 v138, v138, 0x3e0293ee, v0
	v_exp_f32_e32 v138, v138
	v_fmamk_f32 v139, v139, 0x3e0293ee, v0
	v_exp_f32_e32 v139, v139
	ds_read_b64_tr_b16 v[244:245], v221 offset:0x4400
	ds_read_b64_tr_b16 v[246:247], v221 offset:0x4c00
	v_mfma_f32_32x32x16_bf16 v[98:113], v[130:133], v[248:251], v[98:113]
	v_add_f32_e32 v252, v252, v138
	v_fmamk_f32 v140, v140, 0x3e0293ee, v0
	v_exp_f32_e32 v140, v140
	v_add_f32_e32 v252, v252, v139
	v_fmamk_f32 v141, v141, 0x3e0293ee, v0
	ds_read_b64_tr_b16 v[248:249], v221 offset:0x4600
	ds_read_b64_tr_b16 v[250:251], v221 offset:0x4e00
	v_mfma_f32_32x32x16_bf16 v[82:97], v[130:133], v[224:227], v[82:97]
	v_exp_f32_e32 v141, v141
	v_add_f32_e32 v252, v252, v140
	v_fmamk_f32 v142, v142, 0x3e0293ee, v0
	v_exp_f32_e32 v142, v142
	ds_read_b64_tr_b16 v[224:225], v221 offset:0x1000
	ds_read_b64_tr_b16 v[226:227], v221 offset:0x1800
	v_mfma_f32_32x32x16_bf16 v[66:81], v[130:133], v[228:231], v[66:81]
	v_add_f32_e32 v252, v252, v141
	v_fmamk_f32 v143, v143, 0x3e0293ee, v0
	v_exp_f32_e32 v143, v143
	v_add_f32_e32 v252, v252, v142
	v_fmamk_f32 v144, v144, 0x3e0293ee, v0
	ds_read_b64_tr_b16 v[228:229], v221 offset:0x1200
	ds_read_b64_tr_b16 v[230:231], v221 offset:0x1a00
	s_waitcnt lgkmcnt(4)
	v_mfma_f32_32x32x16_bf16 v[50:65], v[130:133], v[232:235], v[50:65]
	v_exp_f32_e32 v144, v144
	v_add_f32_e32 v252, v252, v143
	v_fmamk_f32 v145, v145, 0x3e0293ee, v0
	v_exp_f32_e32 v145, v145
	ds_read_b64_tr_b16 v[232:233], v221 offset:0x1400
	ds_read_b64_tr_b16 v[234:235], v221 offset:0x1c00
	v_mfma_f32_32x32x16_bf16 v[34:49], v[130:133], v[236:239], v[34:49]
	v_add_f32_e32 v252, v252, v144
	v_cvt_pk_bf16_f32 v134, v138, v139
	v_add_f32_e32 v252, v252, v145
	v_cvt_pk_bf16_f32 v135, v140, v141
	v_cvt_pk_bf16_f32 v136, v142, v143
	v_cvt_pk_bf16_f32 v137, v144, v145
	ds_read_b64_tr_b16 v[236:237], v221 offset:0x1600
	ds_read_b64_tr_b16 v[238:239], v221 offset:0x1e00
	v_mfma_f32_32x32x16_bf16 v[18:33], v[130:133], v[244:247], v[18:33]
	s_nop 0
	v_permlane32_swap_b32_e32 v134, v136
	v_permlane32_swap_b32_e32 v135, v137
	v_fmamk_f32 v146, v146, 0x3e0293ee, v0
	v_exp_f32_e32 v146, v146
	ds_read_b64_tr_b16 v[244:245], v221 offset:0x5000
	ds_read_b64_tr_b16 v[246:247], v221 offset:0x5800
	v_mfma_f32_32x32x16_bf16 v[2:17], v[130:133], v[248:251], v[2:17]
	v_fmamk_f32 v147, v147, 0x3e0293ee, v0
	v_exp_f32_e32 v147, v147
	v_add_f32_e32 v252, v252, v146
	v_fmamk_f32 v148, v148, 0x3e0293ee, v0
	ds_read_b64_tr_b16 v[248:249], v221 offset:0x5200
	ds_read_b64_tr_b16 v[250:251], v221 offset:0x5a00
	s_waitcnt lgkmcnt(4)
; __device__ __forceinline__ int crow(int r, int hi) { return (r & 3) + 8 * (r >> 2) + 4 * hi; }
; #define SBAR() __builtin_amdgcn_sched_barrier(0)
; #define PV_MMA(OD, R) do { OD = __builtin_amdgcn_mfma_f32_32x32x16_bf16(pa0, PKF(R[0], R[1]), OD, 0, 0, 0); OD = __builtin_amdgcn_mfma_f32_32x32x16_bf16(pa1, PKF(R[2], R[3]), OD, 0, 0, 0); \
;         OD = __builtin_amdgcn_mfma_f32_32x32x16_bf16(pa2, PKF(R[4], R[5]), OD, 0, 0, 0); OD = __builtin_amdgcn_mfma_f32_32x32x16_bf16(pa3, PKF(R[6], R[7]), OD, 0, 0, 0); SBAR(); } while (0)
; __device__ __forceinline__ void pv256(f32x16* o, int vb, bf16x8 pa0, bf16x8 pa1, bf16x8 pa2, bf16x8 pa3) {
;     s16x4 ra[8], rb[8];
;     asm volatile("s_waitcnt lgkmcnt(0)" ::: "memory");
;     PV_RD8(0, 0, ra);
;     PV_RD8(1, 0, rb); PV_W8(); PV_MMA(o[0], ra);
;     PV_RD8(2, 0, ra); PV_W8(); PV_MMA(o[1], rb);
;     PV_RD8(3, 0, rb); PV_W8(); PV_MMA(o[2], ra);
;     PV_RD8(0, 16384, ra); PV_W8(); PV_MMA(o[3], rb);
;     PV_RD8(1, 16384, rb); PV_W8(); PV_MMA(o[4], ra);
;     PV_RD8(2, 16384, ra); PV_W8(); PV_MMA(o[5], rb);
;     PV_RD8(3, 16384, rb); PV_W8(); PV_MMA(o[6], ra);
;     asm volatile("s_waitcnt lgkmcnt(0)" ::: "memory"); SBAR(); PV_MMA(o[7], rb);
; }
; template <int LDQ, int LDK, int LDV, int LDO>
; __device__ __forceinline__ void attn256_body(const int tid, const bf16_t* __restrict__ Qb, const bf16_t* __restrict__ Kh, const bf16_t* __restrict__ Vh, bf16_t* __restrict__ Ob, int seq, char* lds, LAS unsigned char* ldsl) {
;     ...
;         for (int r = 0; r < 16; ++r) { p0[r] = __builtin_amdgcn_exp2f(fmaf(p0[r], C, mnC)); p1[r] = __builtin_amdgcn_exp2f(fmaf(p1[r], C, mnC)); ps += p0[r] + p1[r]; }
;         { auto rr = __builtin_amdgcn_permlane32_swap(__float_as_uint(ps), __float_as_uint(ps), false, false); ps = __uint_as_float(rr[0]) + __uint_as_float(rr[1]); }
;         l_reg = l_reg * alpha + ps;
;         bf16x8 pa0, pa1, pa2, pa3;
;         PK4(p0, 0, pa0); PK4(p0, 8, pa1); PK4(p1, 0, pa2); PK4(p1, 8, pa3);
;         if (__any(alpha < 1.f)) { if (hi == 0) al_l[r32] = alpha; asm volatile("s_waitcnt lgkmcnt(0)" ::: "memory");
; #pragma unroll
;             for (int r = 0; r < 16; ++r) { const float f = al_l[crow(r, hi)];
; #pragma unroll
;                 for (int d = 0; d < 8; ++d) o[d][r] *= f; } }
;         const int vb = vb0 + b * 32768;
;         pv256(o, vb, pa0, pa1, pa2, pa3);
	v_mfma_f32_32x32x16_bf16 v[114:129], v[134:137], v[224:227], v[114:129]
	v_exp_f32_e32 v148, v148
	v_add_f32_e32 v252, v252, v147
	v_fmamk_f32 v149, v149, 0x3e0293ee, v0
	v_exp_f32_e32 v149, v149
	ds_read_b64_tr_b16 v[224:225], v221 offset:0x5400
	ds_read_b64_tr_b16 v[226:227], v221 offset:0x5c00
	v_mfma_f32_32x32x16_bf16 v[98:113], v[134:137], v[228:231], v[98:113]
	v_add_f32_e32 v252, v252, v148
	v_fmamk_f32 v150, v150, 0x3e0293ee, v0
	v_exp_f32_e32 v150, v150
	v_add_f32_e32 v252, v252, v149
	v_fmamk_f32 v151, v151, 0x3e0293ee, v0
	ds_read_b64_tr_b16 v[228:229], v221 offset:0x5600
	ds_read_b64_tr_b16 v[230:231], v221 offset:0x5e00
	v_mfma_f32_32x32x16_bf16 v[82:97], v[134:137], v[232:235], v[82:97]
	v_exp_f32_e32 v151, v151
	v_add_f32_e32 v252, v252, v150
	v_fmamk_f32 v152, v152, 0x3e0293ee, v0
	v_exp_f32_e32 v152, v152
	ds_read_b64_tr_b16 v[232:233], v221 offset:0x2000
	ds_read_b64_tr_b16 v[234:235], v221 offset:0x2800
	v_mfma_f32_32x32x16_bf16 v[66:81], v[134:137], v[236:239], v[66:81]
	v_add_f32_e32 v252, v252, v151
	v_fmamk_f32 v153, v153, 0x3e0293ee, v0
	v_exp_f32_e32 v153, v153
	v_add_f32_e32 v252, v252, v152
	v_cvt_pk_bf16_f32 v138, v146, v147
	ds_read_b64_tr_b16 v[236:237], v221 offset:0x2200
	ds_read_b64_tr_b16 v[238:239], v221 offset:0x2a00
	s_waitcnt lgkmcnt(4)
	v_mfma_f32_32x32x16_bf16 v[50:65], v[134:137], v[244:247], v[50:65]
	v_add_f32_e32 v252, v252, v153
	v_cvt_pk_bf16_f32 v139, v148, v149
	v_cvt_pk_bf16_f32 v140, v150, v151
	v_cvt_pk_bf16_f32 v141, v152, v153
	s_nop 0
	v_permlane32_swap_b32_e32 v138, v140
	ds_read_b64_tr_b16 v[244:245], v221 offset:0x2400
	ds_read_b64_tr_b16 v[246:247], v221 offset:0x2c00
	v_mfma_f32_32x32x16_bf16 v[34:49], v[134:137], v[248:251], v[34:49]
	v_permlane32_swap_b32_e32 v139, v141
	v_fmamk_f32 v154, v154, 0x3e0293ee, v0
	v_exp_f32_e32 v154, v154
	v_fmamk_f32 v155, v155, 0x3e0293ee, v0
	ds_read_b64_tr_b16 v[248:249], v221 offset:0x2600
	ds_read_b64_tr_b16 v[250:251], v221 offset:0x2e00
	v_mfma_f32_32x32x16_bf16 v[18:33], v[134:137], v[224:227], v[18:33]
	v_exp_f32_e32 v155, v155
	v_add_f32_e32 v252, v252, v154
	v_fmamk_f32 v156, v156, 0x3e0293ee, v0
	v_exp_f32_e32 v156, v156
	ds_read_b64_tr_b16 v[224:225], v221 offset:0x6000
	ds_read_b64_tr_b16 v[226:227], v221 offset:0x6800
	v_mfma_f32_32x32x16_bf16 v[2:17], v[134:137], v[228:231], v[2:17]
	v_add_f32_e32 v252, v252, v155
	v_fmamk_f32 v157, v157, 0x3e0293ee, v0
	v_exp_f32_e32 v157, v157
	v_add_f32_e32 v252, v252, v156
	v_fmamk_f32 v158, v158, 0x3e0293ee, v0
	ds_read_b64_tr_b16 v[228:229], v221 offset:0x6200
	ds_read_b64_tr_b16 v[230:231], v221 offset:0x6a00
	s_waitcnt lgkmcnt(4)
	v_mfma_f32_32x32x16_bf16 v[114:129], v[138:141], v[232:235], v[114:129]
	v_exp_f32_e32 v158, v158
	v_add_f32_e32 v252, v252, v157
	v_fmamk_f32 v159, v159, 0x3e0293ee, v0
	v_exp_f32_e32 v159, v159
	ds_read_b64_tr_b16 v[232:233], v221 offset:0x6400
	ds_read_b64_tr_b16 v[234:235], v221 offset:0x6c00
	v_mfma_f32_32x32x16_bf16 v[98:113], v[138:141], v[236:239], v[98:113]
	v_add_f32_e32 v252, v252, v158
	v_fmamk_f32 v160, v160, 0x3e0293ee, v0
	v_exp_f32_e32 v160, v160
	v_add_f32_e32 v252, v252, v159
	v_fmamk_f32 v161, v161, 0x3e0293ee, v0
	ds_read_b64_tr_b16 v[236:237], v221 offset:0x6600
	ds_read_b64_tr_b16 v[238:239], v221 offset:0x6e00
	v_mfma_f32_32x32x16_bf16 v[82:97], v[138:141], v[244:247], v[82:97]
	v_exp_f32_e32 v161, v161
	v_add_f32_e32 v252, v252, v160
	v_cvt_pk_bf16_f32 v142, v154, v155
	v_add_f32_e32 v252, v252, v161
	v_cvt_pk_bf16_f32 v143, v156, v157
	ds_read_b64_tr_b16 v[244:245], v221 offset:0x3000
	ds_read_b64_tr_b16 v[246:247], v221 offset:0x3800
	v_mfma_f32_32x32x16_bf16 v[66:81], v[138:141], v[248:251], v[66:81]
	v_cvt_pk_bf16_f32 v144, v158, v159
	v_cvt_pk_bf16_f32 v145, v160, v161
	s_nop 0
	v_permlane32_swap_b32_e32 v142, v144
	v_permlane32_swap_b32_e32 v143, v145
	v_mov_b32_e32 v240, v252
	ds_read_b64_tr_b16 v[248:249], v221 offset:0x3200
	ds_read_b64_tr_b16 v[250:251], v221 offset:0x3a00
	s_waitcnt lgkmcnt(4)
	v_mfma_f32_32x32x16_bf16 v[50:65], v[138:141], v[224:227], v[50:65]
	s_nop 1
	v_permlane32_swap_b32_e32 v252, v240
	v_add_f32_e32 v240, v252, v240
	v_fma_f32 v223, v223, v243, v240
	ds_read_b64_tr_b16 v[224:225], v221 offset:0x3400
	ds_read_b64_tr_b16 v[226:227], v221 offset:0x3c00
	v_mfma_f32_32x32x16_bf16 v[34:49], v[138:141], v[228:231], v[34:49]
	ds_read_b64_tr_b16 v[228:229], v221 offset:0x3600
	ds_read_b64_tr_b16 v[230:231], v221 offset:0x3e00
	v_mfma_f32_32x32x16_bf16 v[18:33], v[138:141], v[232:235], v[18:33]
	ds_read_b64_tr_b16 v[232:233], v221 offset:0x7000
	ds_read_b64_tr_b16 v[234:235], v221 offset:0x7800
	v_mfma_f32_32x32x16_bf16 v[2:17], v[138:141], v[236:239], v[2:17]
	ds_read_b64_tr_b16 v[236:237], v221 offset:0x7200
	ds_read_b64_tr_b16 v[238:239], v221 offset:0x7a00
	s_waitcnt lgkmcnt(4)
	v_mfma_f32_32x32x16_bf16 v[114:129], v[142:145], v[244:247], v[114:129]
	ds_read_b64_tr_b16 v[244:245], v221 offset:0x7400
	ds_read_b64_tr_b16 v[246:247], v221 offset:0x7c00
	v_mfma_f32_32x32x16_bf16 v[98:113], v[142:145], v[248:251], v[98:113]
	ds_read_b64_tr_b16 v[248:249], v221 offset:0x7600
	ds_read_b64_tr_b16 v[250:251], v221 offset:0x7e00
	v_mfma_f32_32x32x16_bf16 v[82:97], v[142:145], v[224:227], v[82:97]
	v_mfma_f32_32x32x16_bf16 v[66:81], v[142:145], v[228:231], v[66:81]
	s_waitcnt lgkmcnt(0)
	s_waitcnt vmcnt(0)
	s_barrier
	ds_read_b128 v[224:227], v212 offset:16384
	ds_read_b128 v[228:231], v213 offset:16384
	v_mfma_f32_32x32x16_bf16 v[50:65], v[142:145], v[232:235], v[50:65]
	ds_read_b128 v[232:235], v214 offset:16384
	v_mfma_f32_32x32x16_bf16 v[34:49], v[142:145], v[236:239], v[34:49]
	ds_read_b128 v[236:239], v215 offset:16384
	v_mfma_f32_32x32x16_bf16 v[18:33], v[142:145], v[244:247], v[18:33]
	ds_read_b128 v[244:247], v216 offset:16384
	v_mfma_f32_32x32x16_bf16 v[2:17], v[142:145], v[248:251], v[2:17]
	ds_read_b128 v[248:251], v218 offset:16384
.Lattn_top_b1:
	s_cmp_eq_u32 s23, 63
	s_cbranch_scc1 .Lattn_nodma_b1
	s_mov_b32 m0, s21
	s_nop 0
	global_load_lds_dwordx4 v206, s[6:7]
	s_add_i32 m0, s21, 0x2000
	s_nop 0
	global_load_lds_dwordx4 v204, s[6:7]
	s_add_i32 m0, s21, 0x8000
	s_nop 0
	global_load_lds_dwordx4 v196, s[36:37]
	s_add_i32 m0, s21, 0xa000
	s_nop 0
	global_load_lds_dwordx4 v198, s[36:37]
	s_add_i32 m0, s21, 0xc000
	s_nop 0
	global_load_lds_dwordx4 v200, s[36:37]
	s_add_i32 m0, s21, 0xe000
	s_nop 0
	global_load_lds_dwordx4 v202, s[36:37]

; __device__ __forceinline__ int crow(int r, int hi) { return (r & 3) + 8 * (r >> 2) + 4 * hi; }
; #define SBAR() __builtin_amdgcn_sched_barrier(0)
; #define PV_MMA(OD, R) do { OD = __builtin_amdgcn_mfma_f32_32x32x16_bf16(pa0, PKF(R[0], R[1]), OD, 0, 0, 0); OD = __builtin_amdgcn_mfma_f32_32x32x16_bf16(pa1, PKF(R[2], R[3]), OD, 0, 0, 0); \
;         OD = __builtin_amdgcn_mfma_f32_32x32x16_bf16(pa2, PKF(R[4], R[5]), OD, 0, 0, 0); OD = __builtin_amdgcn_mfma_f32_32x32x16_bf16(pa3, PKF(R[6], R[7]), OD, 0, 0, 0); SBAR(); } while (0)
; __device__ __forceinline__ void pv256(f32x16* o, int vb, bf16x8 pa0, bf16x8 pa1, bf16x8 pa2, bf16x8 pa3) {
;     s16x4 ra[8], rb[8];
;     asm volatile("s_waitcnt lgkmcnt(0)" ::: "memory");
;     PV_RD8(0, 0, ra);
;     PV_RD8(1, 0, rb); PV_W8(); PV_MMA(o[0], ra);
;     PV_RD8(2, 0, ra); PV_W8(); PV_MMA(o[1], rb);
;     PV_RD8(3, 0, rb); PV_W8(); PV_MMA(o[2], ra);
;     PV_RD8(0, 16384, ra); PV_W8(); PV_MMA(o[3], rb);
;     PV_RD8(1, 16384, rb); PV_W8(); PV_MMA(o[4], ra);
;     PV_RD8(2, 16384, ra); PV_W8(); PV_MMA(o[5], rb);
;     PV_RD8(3, 16384, rb); PV_W8(); PV_MMA(o[6], ra);
;     asm volatile("s_waitcnt lgkmcnt(0)" ::: "memory"); SBAR(); PV_MMA(o[7], rb);
; }
; template <int LDQ, int LDK, int LDV, int LDO>
; __device__ __forceinline__ void attn256_body(const int tid, const bf16_t* __restrict__ Qb, const bf16_t* __restrict__ Kh, const bf16_t* __restrict__ Vh, bf16_t* __restrict__ Ob, int seq, char* lds, LAS unsigned char* ldsl) {
;     ...
;         for (int r = 0; r < 16; ++r) { p0[r] = __builtin_amdgcn_exp2f(fmaf(p0[r], C, mnC)); p1[r] = __builtin_amdgcn_exp2f(fmaf(p1[r], C, mnC)); ps += p0[r] + p1[r]; }
;         { auto rr = __builtin_amdgcn_permlane32_swap(__float_as_uint(ps), __float_as_uint(ps), false, false); ps = __uint_as_float(rr[0]) + __uint_as_float(rr[1]); }
;         l_reg = l_reg * alpha + ps;
;         bf16x8 pa0, pa1, pa2, pa3;
;         PK4(p0, 0, pa0); PK4(p0, 8, pa1); PK4(p1, 0, pa2); PK4(p1, 8, pa3);
;         if (__any(alpha < 1.f)) { if (hi == 0) al_l[r32] = alpha; asm volatile("s_waitcnt lgkmcnt(0)" ::: "memory");
; #pragma unroll
;             for (int r = 0; r < 16; ++r) { const float f = al_l[crow(r, hi)];
; #pragma unroll
;                 for (int d = 0; d < 8; ++d) o[d][r] *= f; } }
;         const int vb = vb0 + b * 32768;
;         pv256(o, vb, pa0, pa1, pa2, pa3);
.Lattn_resc_done_b1:
	v_exp_f32_e32 v130, v130
	v_exp_f32_e32 v131, v131
	v_exp_f32_e32 v132, v132
	v_exp_f32_e32 v133, v133
	v_exp_f32_e32 v134, v134
	v_exp_f32_e32 v135, v135
	v_exp_f32_e32 v136, v136
	v_exp_f32_e32 v137, v137
	v_add_f32_e32 v252, v130, v131
	v_cvt_pk_bf16_f32 v130, v130, v131
	v_add_f32_e32 v208, v132, v133
	v_cvt_pk_bf16_f32 v131, v132, v133
	v_add_f32_e32 v209, v134, v135
	v_cvt_pk_bf16_f32 v132, v134, v135
	v_add_f32_e32 v240, v136, v137
	v_cvt_pk_bf16_f32 v133, v136, v137
	s_nop 0
	v_permlane32_swap_b32_e32 v130, v132
	v_permlane32_swap_b32_e32 v131, v133
	v_add_f32_e32 v252, v252, v208
	v_add_f32_e32 v209, v209, v240
	v_add_f32_e32 v252, v252, v209
	s_waitcnt lgkmcnt(4)
	v_mfma_f32_32x32x16_bf16 v[114:129], v[130:133], v[244:247], v[114:129]
	v_fmamk_f32 v138, v138, 0x3e0293ee, v0
	v_exp_f32_e32 v138, v138
	v_fmamk_f32 v139, v139, 0x3e0293ee, v0
	v_exp_f32_e32 v139, v139
	ds_read_b64_tr_b16 v[244:245], v221 offset:0xc400
	ds_read_b64_tr_b16 v[246:247], v221 offset:0xcc00
	v_mfma_f32_32x32x16_bf16 v[98:113], v[130:133], v[248:251], v[98:113]
	v_add_f32_e32 v252, v252, v138
	v_fmamk_f32 v140, v140, 0x3e0293ee, v0
	v_exp_f32_e32 v140, v140
	v_add_f32_e32 v252, v252, v139
	v_fmamk_f32 v141, v141, 0x3e0293ee, v0
	ds_read_b64_tr_b16 v[248:249], v221 offset:0xc600
	ds_read_b64_tr_b16 v[250:251], v221 offset:0xce00
	v_mfma_f32_32x32x16_bf16 v[82:97], v[130:133], v[224:227], v[82:97]
	v_exp_f32_e32 v141, v141
	v_add_f32_e32 v252, v252, v140
	v_fmamk_f32 v142, v142, 0x3e0293ee, v0
	v_exp_f32_e32 v142, v142
	ds_read_b64_tr_b16 v[224:225], v221 offset:0x9000
	ds_read_b64_tr_b16 v[226:227], v221 offset:0x9800
	v_mfma_f32_32x32x16_bf16 v[66:81], v[130:133], v[228:231], v[66:81]
	v_add_f32_e32 v252, v252, v141
	v_fmamk_f32 v143, v143, 0x3e0293ee, v0
	v_exp_f32_e32 v143, v143
	v_add_f32_e32 v252, v252, v142
	v_fmamk_f32 v144, v144, 0x3e0293ee, v0
	ds_read_b64_tr_b16 v[228:229], v221 offset:0x9200
	ds_read_b64_tr_b16 v[230:231], v221 offset:0x9a00
	s_waitcnt lgkmcnt(4)
	v_mfma_f32_32x32x16_bf16 v[50:65], v[130:133], v[232:235], v[50:65]
	v_exp_f32_e32 v144, v144
	v_add_f32_e32 v252, v252, v143
	v_fmamk_f32 v145, v145, 0x3e0293ee, v0
	v_exp_f32_e32 v145, v145
	ds_read_b64_tr_b16 v[232:233], v221 offset:0x9400
	ds_read_b64_tr_b16 v[234:235], v221 offset:0x9c00
	v_mfma_f32_32x32x16_bf16 v[34:49], v[130:133], v[236:239], v[34:49]
	v_add_f32_e32 v252, v252, v144
	v_cvt_pk_bf16_f32 v134, v138, v139
	v_add_f32_e32 v252, v252, v145
	v_cvt_pk_bf16_f32 v135, v140, v141
	v_cvt_pk_bf16_f32 v136, v142, v143
	v_cvt_pk_bf16_f32 v137, v144, v145
	ds_read_b64_tr_b16 v[236:237], v221 offset:0x9600
	ds_read_b64_tr_b16 v[238:239], v221 offset:0x9e00
	v_mfma_f32_32x32x16_bf16 v[18:33], v[130:133], v[244:247], v[18:33]
	s_nop 0
	v_permlane32_swap_b32_e32 v134, v136
	v_permlane32_swap_b32_e32 v135, v137
	v_fmamk_f32 v146, v146, 0x3e0293ee, v0
	v_exp_f32_e32 v146, v146
	ds_read_b64_tr_b16 v[244:245], v221 offset:0xd000
	ds_read_b64_tr_b16 v[246:247], v221 offset:0xd800
	v_mfma_f32_32x32x16_bf16 v[2:17], v[130:133], v[248:251], v[2:17]
	v_fmamk_f32 v147, v147, 0x3e0293ee, v0
	v_exp_f32_e32 v147, v147
	v_add_f32_e32 v252, v252, v146
	v_fmamk_f32 v148, v148, 0x3e0293ee, v0
	ds_read_b64_tr_b16 v[248:249], v221 offset:0xd200
	ds_read_b64_tr_b16 v[250:251], v221 offset:0xda00
	s_waitcnt lgkmcnt(4)
	v_mfma_f32_32x32x16_bf16 v[114:129], v[134:137], v[224:227], v[114:129]
	v_exp_f32_e32 v148, v148
	v_add_f32_e32 v252, v252, v147
	v_fmamk_f32 v149, v149, 0x3e0293ee, v0
	v_exp_f32_e32 v149, v149
	ds_read_b64_tr_b16 v[224:225], v221 offset:0xd400
	ds_read_b64_tr_b16 v[226:227], v221 offset:0xdc00
	v_mfma_f32_32x32x16_bf16 v[98:113], v[134:137], v[228:231], v[98:113]
	v_add_f32_e32 v252, v252, v148
	v_fmamk_f32 v150, v150, 0x3e0293ee, v0
	v_exp_f32_e32 v150, v150
	v_add_f32_e32 v252, v252, v149
	v_fmamk_f32 v151, v151, 0x3e0293ee, v0
	ds_read_b64_tr_b16 v[228:229], v221 offset:0xd600
	ds_read_b64_tr_b16 v[230:231], v221 offset:0xde00
	v_mfma_f32_32x32x16_bf16 v[82:97], v[134:137], v[232:235], v[82:97]
	v_exp_f32_e32 v151, v151
	v_add_f32_e32 v252, v252, v150
	v_fmamk_f32 v152, v152, 0x3e0293ee, v0
	v_exp_f32_e32 v152, v152
	ds_read_b64_tr_b16 v[232:233], v221 offset:0xa000
	ds_read_b64_tr_b16 v[234:235], v221 offset:0xa800
	v_mfma_f32_32x32x16_bf16 v[66:81], v[134:137], v[236:239], v[66:81]
	v_add_f32_e32 v252, v252, v151
	v_fmamk_f32 v153, v153, 0x3e0293ee, v0
	v_exp_f32_e32 v153, v153
	v_add_f32_e32 v252, v252, v152
	v_cvt_pk_bf16_f32 v138, v146, v147
	ds_read_b64_tr_b16 v[236:237], v221 offset:0xa200
	ds_read_b64_tr_b16 v[238:239], v221 offset:0xaa00
	s_waitcnt lgkmcnt(4)
; #define SBAR() __builtin_amdgcn_sched_barrier(0)
; #define PV_MMA(OD, R) do { OD = __builtin_amdgcn_mfma_f32_32x32x16_bf16(pa0, PKF(R[0], R[1]), OD, 0, 0, 0); OD = __builtin_amdgcn_mfma_f32_32x32x16_bf16(pa1, PKF(R[2], R[3]), OD, 0, 0, 0); \
;         OD = __builtin_amdgcn_mfma_f32_32x32x16_bf16(pa2, PKF(R[4], R[5]), OD, 0, 0, 0); OD = __builtin_amdgcn_mfma_f32_32x32x16_bf16(pa3, PKF(R[6], R[7]), OD, 0, 0, 0); SBAR(); } while (0)
; #define PV_W8() do { asm volatile("s_waitcnt lgkmcnt(8)" ::: "memory"); SBAR(); } while (0)
; __device__ __forceinline__ void pv256(f32x16* o, int vb, bf16x8 pa0, bf16x8 pa1, bf16x8 pa2, bf16x8 pa3) {
;     s16x4 ra[8], rb[8];
;     asm volatile("s_waitcnt lgkmcnt(0)" ::: "memory");
;     PV_RD8(0, 0, ra);
;     PV_RD8(1, 0, rb); PV_W8(); PV_MMA(o[0], ra);
;     PV_RD8(2, 0, ra); PV_W8(); PV_MMA(o[1], rb);
;     PV_RD8(3, 0, rb); PV_W8(); PV_MMA(o[2], ra);
;     PV_RD8(0, 16384, ra); PV_W8(); PV_MMA(o[3], rb);
;     PV_RD8(1, 16384, rb); PV_W8(); PV_MMA(o[4], ra);
;     PV_RD8(2, 16384, ra); PV_W8(); PV_MMA(o[5], rb);
;     PV_RD8(3, 16384, rb); PV_W8(); PV_MMA(o[6], ra);
;     asm volatile("s_waitcnt lgkmcnt(0)" ::: "memory"); SBAR(); PV_MMA(o[7], rb);
; }
; template <int LDQ, int LDK, int LDV, int LDO>
; __device__ __forceinline__ void attn256_body(const int tid, const bf16_t* __restrict__ Qb, const bf16_t* __restrict__ Kh, const bf16_t* __restrict__ Vh, bf16_t* __restrict__ Ob, int seq, char* lds, LAS unsigned char* ldsl) {
;     ...
;     for (int j = 0; j < NT; ++j) {
;         const int b = j & 1;
;         asm volatile("s_waitcnt vmcnt(0)" ::: "memory"); __builtin_amdgcn_s_barrier(); asm volatile("" ::: "memory");
;         if (j + 1 < NT) A2_ISSUE(j + 1, b ^ 1);
;         f32x16 p0, p1;
;         qkt(p0, p1, lds + A2_KOFF + b * 16384, qr, r32, hi);
	v_mfma_f32_32x32x16_bf16 v[50:65], v[134:137], v[244:247], v[50:65]
	v_add_f32_e32 v252, v252, v153
	v_cvt_pk_bf16_f32 v139, v148, v149
	v_cvt_pk_bf16_f32 v140, v150, v151
	v_cvt_pk_bf16_f32 v141, v152, v153
	s_nop 0
	v_permlane32_swap_b32_e32 v138, v140
	ds_read_b64_tr_b16 v[244:245], v221 offset:0xa400
	ds_read_b64_tr_b16 v[246:247], v221 offset:0xac00
	v_mfma_f32_32x32x16_bf16 v[34:49], v[134:137], v[248:251], v[34:49]
	v_permlane32_swap_b32_e32 v139, v141
	v_fmamk_f32 v154, v154, 0x3e0293ee, v0
	v_exp_f32_e32 v154, v154
	v_fmamk_f32 v155, v155, 0x3e0293ee, v0
	ds_read_b64_tr_b16 v[248:249], v221 offset:0xa600
	ds_read_b64_tr_b16 v[250:251], v221 offset:0xae00
	v_mfma_f32_32x32x16_bf16 v[18:33], v[134:137], v[224:227], v[18:33]
	v_exp_f32_e32 v155, v155
	v_add_f32_e32 v252, v252, v154
	v_fmamk_f32 v156, v156, 0x3e0293ee, v0
	v_exp_f32_e32 v156, v156
	ds_read_b64_tr_b16 v[224:225], v221 offset:0xe000
	ds_read_b64_tr_b16 v[226:227], v221 offset:0xe800
	v_mfma_f32_32x32x16_bf16 v[2:17], v[134:137], v[228:231], v[2:17]
	v_add_f32_e32 v252, v252, v155
	v_fmamk_f32 v157, v157, 0x3e0293ee, v0
	v_exp_f32_e32 v157, v157
	v_add_f32_e32 v252, v252, v156
	v_fmamk_f32 v158, v158, 0x3e0293ee, v0
	ds_read_b64_tr_b16 v[228:229], v221 offset:0xe200
	ds_read_b64_tr_b16 v[230:231], v221 offset:0xea00
	s_waitcnt lgkmcnt(4)
	v_mfma_f32_32x32x16_bf16 v[114:129], v[138:141], v[232:235], v[114:129]
	v_exp_f32_e32 v158, v158
	v_add_f32_e32 v252, v252, v157
	v_fmamk_f32 v159, v159, 0x3e0293ee, v0
	v_exp_f32_e32 v159, v159
	ds_read_b64_tr_b16 v[232:233], v221 offset:0xe400
	ds_read_b64_tr_b16 v[234:235], v221 offset:0xec00
	v_mfma_f32_32x32x16_bf16 v[98:113], v[138:141], v[236:239], v[98:113]
	v_add_f32_e32 v252, v252, v158
	v_fmamk_f32 v160, v160, 0x3e0293ee, v0
	v_exp_f32_e32 v160, v160
	v_add_f32_e32 v252, v252, v159
	v_fmamk_f32 v161, v161, 0x3e0293ee, v0
	ds_read_b64_tr_b16 v[236:237], v221 offset:0xe600
	ds_read_b64_tr_b16 v[238:239], v221 offset:0xee00
	v_mfma_f32_32x32x16_bf16 v[82:97], v[138:141], v[244:247], v[82:97]
	v_exp_f32_e32 v161, v161
	v_add_f32_e32 v252, v252, v160
	v_cvt_pk_bf16_f32 v142, v154, v155
	v_add_f32_e32 v252, v252, v161
	v_cvt_pk_bf16_f32 v143, v156, v157
	ds_read_b64_tr_b16 v[244:245], v221 offset:0xb000
	ds_read_b64_tr_b16 v[246:247], v221 offset:0xb800
	v_mfma_f32_32x32x16_bf16 v[66:81], v[138:141], v[248:251], v[66:81]
	v_cvt_pk_bf16_f32 v144, v158, v159
	v_cvt_pk_bf16_f32 v145, v160, v161
	s_nop 0
	v_permlane32_swap_b32_e32 v142, v144
	v_permlane32_swap_b32_e32 v143, v145
	v_mov_b32_e32 v240, v252
	ds_read_b64_tr_b16 v[248:249], v221 offset:0xb200
	ds_read_b64_tr_b16 v[250:251], v221 offset:0xba00
	s_waitcnt lgkmcnt(4)
	v_mfma_f32_32x32x16_bf16 v[50:65], v[138:141], v[224:227], v[50:65]
	s_nop 1
	v_permlane32_swap_b32_e32 v252, v240
	v_add_f32_e32 v240, v252, v240
	v_fma_f32 v223, v223, v243, v240
	ds_read_b64_tr_b16 v[224:225], v221 offset:0xb400
	ds_read_b64_tr_b16 v[226:227], v221 offset:0xbc00
	v_mfma_f32_32x32x16_bf16 v[34:49], v[138:141], v[228:231], v[34:49]
	ds_read_b64_tr_b16 v[228:229], v221 offset:0xb600
	ds_read_b64_tr_b16 v[230:231], v221 offset:0xbe00
	v_mfma_f32_32x32x16_bf16 v[18:33], v[138:141], v[232:235], v[18:33]
	ds_read_b64_tr_b16 v[232:233], v221 offset:0xf000
	ds_read_b64_tr_b16 v[234:235], v221 offset:0xf800
	v_mfma_f32_32x32x16_bf16 v[2:17], v[138:141], v[236:239], v[2:17]
	ds_read_b64_tr_b16 v[236:237], v221 offset:0xf200
	ds_read_b64_tr_b16 v[238:239], v221 offset:0xfa00
	s_waitcnt lgkmcnt(4)
	v_mfma_f32_32x32x16_bf16 v[114:129], v[142:145], v[244:247], v[114:129]
	ds_read_b64_tr_b16 v[244:245], v221 offset:0xf400
	ds_read_b64_tr_b16 v[246:247], v221 offset:0xfc00
	v_mfma_f32_32x32x16_bf16 v[98:113], v[142:145], v[248:251], v[98:113]
	ds_read_b64_tr_b16 v[248:249], v221 offset:0xf600
	ds_read_b64_tr_b16 v[250:251], v221 offset:0xfe00
	v_mfma_f32_32x32x16_bf16 v[82:97], v[142:145], v[224:227], v[82:97]
	v_mfma_f32_32x32x16_bf16 v[66:81], v[142:145], v[228:231], v[66:81]
	s_waitcnt lgkmcnt(0)
	s_waitcnt vmcnt(0)
	s_barrier
	ds_read_b128 v[224:227], v212
	ds_read_b128 v[228:231], v213
	v_mfma_f32_32x32x16_bf16 v[50:65], v[142:145], v[232:235], v[50:65]
	ds_read_b128 v[232:235], v214
	v_mfma_f32_32x32x16_bf16 v[34:49], v[142:145], v[236:239], v[34:49]
	ds_read_b128 v[236:239], v215
	v_mfma_f32_32x32x16_bf16 v[18:33], v[142:145], v[244:247], v[18:33]
	ds_read_b128 v[244:247], v216
	v_mfma_f32_32x32x16_bf16 v[2:17], v[142:145], v[248:251], v[2:17]
	ds_read_b128 v[248:251], v218
	s_cmp_eq_u32 s23, 64
	s_cbranch_scc0 .LBB0_134
	s_waitcnt lgkmcnt(0)
	v_mov_b32_e32 v146, v223
	s_branch .LBB0_143
